# v10 plus: residual-GEMM epilogues (H += scale*acc) re-emitted with 12/12/8 loads in flight instead of 32 serial load-wait-store round trips
# speedup vs baseline: 1.0616x; 1.0046x over previous
.LBB0_267:
	v_lshl_add_u32 v148, s29, 8, v151
	v_lshl_or_b32 v144, s28, 8, v153
	v_ashrrev_i32_e32 v149, 31, v148
	v_ashrrev_i32_e32 v145, 31, v144
	v_lshlrev_b64 v[146:147], 12, v[148:149]
	v_lshl_add_u64 v[156:157], v[128:129], 0, v[146:147]
	v_lshlrev_b64 v[146:147], 2, v[144:145]
	v_lshl_add_u64 v[144:145], v[156:157], 0, v[146:147]
	v_add_co_u32_e32 v228, vcc, 0x10000, v144
	s_nop 1
	v_addc_co_u32_e32 v229, vcc, 0, v145, vcc
	v_add_co_u32_e32 v230, vcc, 0x20000, v144
	s_nop 1
	v_addc_co_u32_e32 v231, vcc, 0, v145, vcc
	global_load_dwordx4 v[156:159], v[144:145], off
	global_load_dwordx4 v[170:173], v[144:145], off offset:64
	global_load_dwordx4 v[174:177], v[144:145], off offset:512
	global_load_dwordx4 v[178:181], v[144:145], off offset:576
	global_load_dwordx4 v[182:185], v[228:229], off
	global_load_dwordx4 v[198:201], v[228:229], off offset:64
	global_load_dwordx4 v[202:205], v[228:229], off offset:512
	global_load_dwordx4 v[206:209], v[228:229], off offset:576
	global_load_dwordx4 v[210:213], v[230:231], off
	global_load_dwordx4 v[214:217], v[230:231], off offset:64
	global_load_dwordx4 v[218:221], v[230:231], off offset:512
	global_load_dwordx4 v[222:225], v[230:231], off offset:576
	s_waitcnt vmcnt(11)
	v_pk_fma_f32 v[126:127], v[126:127], 0.5, v[158:159] op_sel_hi:[1,0,1]
	v_pk_fma_f32 v[124:125], v[124:125], 0.5, v[156:157] op_sel_hi:[1,0,1]
	global_store_dwordx4 v[144:145], v[124:127], off
	s_waitcnt vmcnt(11)
	v_pk_fma_f32 v[122:123], v[122:123], 0.5, v[172:173] op_sel_hi:[1,0,1]
	v_pk_fma_f32 v[120:121], v[120:121], 0.5, v[170:171] op_sel_hi:[1,0,1]
	global_store_dwordx4 v[144:145], v[120:123], off offset:64
	s_waitcnt vmcnt(11)
	v_pk_fma_f32 v[118:119], v[118:119], 0.5, v[176:177] op_sel_hi:[1,0,1]
	v_pk_fma_f32 v[116:117], v[116:117], 0.5, v[174:175] op_sel_hi:[1,0,1]
	global_store_dwordx4 v[144:145], v[116:119], off offset:512
	s_waitcnt vmcnt(11)
	v_pk_fma_f32 v[114:115], v[114:115], 0.5, v[180:181] op_sel_hi:[1,0,1]
	v_pk_fma_f32 v[112:113], v[112:113], 0.5, v[178:179] op_sel_hi:[1,0,1]
	global_store_dwordx4 v[144:145], v[112:115], off offset:576
	s_waitcnt vmcnt(11)
	v_pk_fma_f32 v[110:111], v[110:111], 0.5, v[184:185] op_sel_hi:[1,0,1]
	v_pk_fma_f32 v[108:109], v[108:109], 0.5, v[182:183] op_sel_hi:[1,0,1]
	global_store_dwordx4 v[228:229], v[108:111], off
	s_waitcnt vmcnt(11)
	v_pk_fma_f32 v[106:107], v[106:107], 0.5, v[200:201] op_sel_hi:[1,0,1]
	v_pk_fma_f32 v[104:105], v[104:105], 0.5, v[198:199] op_sel_hi:[1,0,1]
	global_store_dwordx4 v[228:229], v[104:107], off offset:64
	s_waitcnt vmcnt(11)
	v_pk_fma_f32 v[102:103], v[102:103], 0.5, v[204:205] op_sel_hi:[1,0,1]
	v_pk_fma_f32 v[100:101], v[100:101], 0.5, v[202:203] op_sel_hi:[1,0,1]
	global_store_dwordx4 v[228:229], v[100:103], off offset:512
	s_waitcnt vmcnt(11)
	v_pk_fma_f32 v[98:99], v[98:99], 0.5, v[208:209] op_sel_hi:[1,0,1]
	v_pk_fma_f32 v[96:97], v[96:97], 0.5, v[206:207] op_sel_hi:[1,0,1]
	global_store_dwordx4 v[228:229], v[96:99], off offset:576
	s_waitcnt vmcnt(11)
	v_pk_fma_f32 v[94:95], v[94:95], 0.5, v[212:213] op_sel_hi:[1,0,1]
	v_pk_fma_f32 v[92:93], v[92:93], 0.5, v[210:211] op_sel_hi:[1,0,1]
	global_store_dwordx4 v[230:231], v[92:95], off
	s_waitcnt vmcnt(11)
	v_pk_fma_f32 v[90:91], v[90:91], 0.5, v[216:217] op_sel_hi:[1,0,1]
	v_pk_fma_f32 v[88:89], v[88:89], 0.5, v[214:215] op_sel_hi:[1,0,1]
	global_store_dwordx4 v[230:231], v[88:91], off offset:64
	s_waitcnt vmcnt(11)
	v_pk_fma_f32 v[86:87], v[86:87], 0.5, v[220:221] op_sel_hi:[1,0,1]
	v_pk_fma_f32 v[84:85], v[84:85], 0.5, v[218:219] op_sel_hi:[1,0,1]
	global_store_dwordx4 v[230:231], v[84:87], off offset:512
	s_waitcnt vmcnt(11)
	v_pk_fma_f32 v[82:83], v[82:83], 0.5, v[224:225] op_sel_hi:[1,0,1]
	v_pk_fma_f32 v[80:81], v[80:81], 0.5, v[222:223] op_sel_hi:[1,0,1]
	global_store_dwordx4 v[230:231], v[80:83], off offset:576
	v_add_co_u32_e32 v226, vcc, 0x30000, v144
	s_nop 1
	v_addc_co_u32_e32 v227, vcc, 0, v145, vcc
	v_add_co_u32_e32 v228, vcc, 0x80000, v144
	s_nop 1
	v_addc_co_u32_e32 v229, vcc, 0, v145, vcc
	v_add_co_u32_e32 v230, vcc, 0x90000, v144
	s_nop 1
	v_addc_co_u32_e32 v231, vcc, 0, v145, vcc
	global_load_dwordx4 v[156:159], v[226:227], off
	global_load_dwordx4 v[170:173], v[226:227], off offset:64
	global_load_dwordx4 v[174:177], v[226:227], off offset:512
	global_load_dwordx4 v[178:181], v[226:227], off offset:576
	global_load_dwordx4 v[182:185], v[228:229], off
	global_load_dwordx4 v[198:201], v[228:229], off offset:64
	global_load_dwordx4 v[202:205], v[228:229], off offset:512
	global_load_dwordx4 v[206:209], v[228:229], off offset:576
	global_load_dwordx4 v[210:213], v[230:231], off
	global_load_dwordx4 v[214:217], v[230:231], off offset:64
	global_load_dwordx4 v[218:221], v[230:231], off offset:512
	global_load_dwordx4 v[222:225], v[230:231], off offset:576
	s_waitcnt vmcnt(11)
	v_pk_fma_f32 v[78:79], v[78:79], 0.5, v[158:159] op_sel_hi:[1,0,1]
	v_pk_fma_f32 v[76:77], v[76:77], 0.5, v[156:157] op_sel_hi:[1,0,1]
	global_store_dwordx4 v[226:227], v[76:79], off
	s_waitcnt vmcnt(11)
	v_pk_fma_f32 v[74:75], v[74:75], 0.5, v[172:173] op_sel_hi:[1,0,1]
	v_pk_fma_f32 v[72:73], v[72:73], 0.5, v[170:171] op_sel_hi:[1,0,1]
	global_store_dwordx4 v[226:227], v[72:75], off offset:64
	s_waitcnt vmcnt(11)
	v_pk_fma_f32 v[70:71], v[70:71], 0.5, v[176:177] op_sel_hi:[1,0,1]
	v_pk_fma_f32 v[68:69], v[68:69], 0.5, v[174:175] op_sel_hi:[1,0,1]
	global_store_dwordx4 v[226:227], v[68:71], off offset:512
	s_waitcnt vmcnt(11)
	v_pk_fma_f32 v[66:67], v[66:67], 0.5, v[180:181] op_sel_hi:[1,0,1]
	v_pk_fma_f32 v[64:65], v[64:65], 0.5, v[178:179] op_sel_hi:[1,0,1]
	global_store_dwordx4 v[226:227], v[64:67], off offset:576
	s_waitcnt vmcnt(11)
	v_pk_fma_f32 v[62:63], v[62:63], 0.5, v[184:185] op_sel_hi:[1,0,1]
	v_pk_fma_f32 v[60:61], v[60:61], 0.5, v[182:183] op_sel_hi:[1,0,1]
	global_store_dwordx4 v[228:229], v[60:63], off
	s_waitcnt vmcnt(11)
	v_pk_fma_f32 v[58:59], v[58:59], 0.5, v[200:201] op_sel_hi:[1,0,1]
	v_pk_fma_f32 v[56:57], v[56:57], 0.5, v[198:199] op_sel_hi:[1,0,1]
	global_store_dwordx4 v[228:229], v[56:59], off offset:64
	s_waitcnt vmcnt(11)
	v_pk_fma_f32 v[54:55], v[54:55], 0.5, v[204:205] op_sel_hi:[1,0,1]
	v_pk_fma_f32 v[52:53], v[52:53], 0.5, v[202:203] op_sel_hi:[1,0,1]
	global_store_dwordx4 v[228:229], v[52:55], off offset:512
	s_waitcnt vmcnt(11)
	v_pk_fma_f32 v[50:51], v[50:51], 0.5, v[208:209] op_sel_hi:[1,0,1]
	v_pk_fma_f32 v[48:49], v[48:49], 0.5, v[206:207] op_sel_hi:[1,0,1]
	global_store_dwordx4 v[228:229], v[48:51], off offset:576
	s_waitcnt vmcnt(11)
	v_pk_fma_f32 v[46:47], v[46:47], 0.5, v[212:213] op_sel_hi:[1,0,1]
	v_pk_fma_f32 v[44:45], v[44:45], 0.5, v[210:211] op_sel_hi:[1,0,1]
	global_store_dwordx4 v[230:231], v[44:47], off
	s_waitcnt vmcnt(11)
	v_pk_fma_f32 v[42:43], v[42:43], 0.5, v[216:217] op_sel_hi:[1,0,1]
	v_pk_fma_f32 v[40:41], v[40:41], 0.5, v[214:215] op_sel_hi:[1,0,1]
	global_store_dwordx4 v[230:231], v[40:43], off offset:64
	s_waitcnt vmcnt(11)
	v_pk_fma_f32 v[38:39], v[38:39], 0.5, v[220:221] op_sel_hi:[1,0,1]
	v_pk_fma_f32 v[36:37], v[36:37], 0.5, v[218:219] op_sel_hi:[1,0,1]
	global_store_dwordx4 v[230:231], v[36:39], off offset:512
	s_waitcnt vmcnt(11)
	v_pk_fma_f32 v[34:35], v[34:35], 0.5, v[224:225] op_sel_hi:[1,0,1]
	v_pk_fma_f32 v[32:33], v[32:33], 0.5, v[222:223] op_sel_hi:[1,0,1]
	global_store_dwordx4 v[230:231], v[32:35], off offset:576
	v_add_co_u32_e32 v226, vcc, 0xa0000, v144
	s_nop 1
	v_addc_co_u32_e32 v227, vcc, 0, v145, vcc
	v_add_co_u32_e32 v228, vcc, 0xb0000, v144
	s_nop 1
	v_addc_co_u32_e32 v229, vcc, 0, v145, vcc
	global_load_dwordx4 v[156:159], v[226:227], off
	global_load_dwordx4 v[170:173], v[226:227], off offset:64
	global_load_dwordx4 v[174:177], v[226:227], off offset:512
	global_load_dwordx4 v[178:181], v[226:227], off offset:576
	global_load_dwordx4 v[182:185], v[228:229], off
	global_load_dwordx4 v[198:201], v[228:229], off offset:64
	global_load_dwordx4 v[202:205], v[228:229], off offset:512
	global_load_dwordx4 v[206:209], v[228:229], off offset:576
	s_waitcnt vmcnt(7)
	v_pk_fma_f32 v[30:31], v[30:31], 0.5, v[158:159] op_sel_hi:[1,0,1]
	v_pk_fma_f32 v[28:29], v[28:29], 0.5, v[156:157] op_sel_hi:[1,0,1]
	global_store_dwordx4 v[226:227], v[28:31], off
	s_waitcnt vmcnt(7)
	v_pk_fma_f32 v[26:27], v[26:27], 0.5, v[172:173] op_sel_hi:[1,0,1]
	v_pk_fma_f32 v[24:25], v[24:25], 0.5, v[170:171] op_sel_hi:[1,0,1]
	global_store_dwordx4 v[226:227], v[24:27], off offset:64
	s_waitcnt vmcnt(7)
	v_pk_fma_f32 v[22:23], v[22:23], 0.5, v[176:177] op_sel_hi:[1,0,1]
	v_pk_fma_f32 v[20:21], v[20:21], 0.5, v[174:175] op_sel_hi:[1,0,1]
	global_store_dwordx4 v[226:227], v[20:23], off offset:512
	s_waitcnt vmcnt(7)
	v_pk_fma_f32 v[18:19], v[18:19], 0.5, v[180:181] op_sel_hi:[1,0,1]
	v_pk_fma_f32 v[16:17], v[16:17], 0.5, v[178:179] op_sel_hi:[1,0,1]
	global_store_dwordx4 v[226:227], v[16:19], off offset:576
	s_waitcnt vmcnt(7)
	v_pk_fma_f32 v[14:15], v[14:15], 0.5, v[184:185] op_sel_hi:[1,0,1]
	v_pk_fma_f32 v[12:13], v[12:13], 0.5, v[182:183] op_sel_hi:[1,0,1]
	global_store_dwordx4 v[228:229], v[12:15], off
	s_waitcnt vmcnt(7)
	v_pk_fma_f32 v[10:11], v[10:11], 0.5, v[200:201] op_sel_hi:[1,0,1]
	v_pk_fma_f32 v[8:9], v[8:9], 0.5, v[198:199] op_sel_hi:[1,0,1]
	global_store_dwordx4 v[228:229], v[8:11], off offset:64
	s_waitcnt vmcnt(7)
	v_pk_fma_f32 v[6:7], v[6:7], 0.5, v[204:205] op_sel_hi:[1,0,1]
	v_pk_fma_f32 v[4:5], v[4:5], 0.5, v[202:203] op_sel_hi:[1,0,1]
	global_store_dwordx4 v[228:229], v[4:7], off offset:512
	s_waitcnt vmcnt(7)
	v_pk_fma_f32 v[2:3], v[2:3], 0.5, v[208:209] op_sel_hi:[1,0,1]
	v_pk_fma_f32 v[0:1], v[0:1], 0.5, v[206:207] op_sel_hi:[1,0,1]
	global_store_dwordx4 v[228:229], v[0:3], off offset:576
	s_mov_b64 s[2:3], 0x80000
	s_mov_b32 s44, 0xfffc0080
	s_mov_b32 s45, -1
	s_mov_b64 s[2:3], 0x90000
	s_mov_b64 s[2:3], 0xa0000
	s_mov_b32 s2, 0xa0000
	s_mov_b64 s[2:3], 0xb0000
	s_mov_b32 s2, 0xb0000
	s_mov_b64 s[2:3], -1
	s_and_b64 vcc, exec, s[4:5]
	s_cbranch_vccnz .LBB0_252
	s_andn2_b64 vcc, exec, s[8:9]
	s_cbranch_vccnz .LBB0_251
	s_barrier
	s_branch .LBB0_251

.LBB0_1617:
	v_lshl_add_u32 v148, s12, 8, v155
	v_lshl_or_b32 v144, s13, 8, v157
	v_ashrrev_i32_e32 v149, 31, v148
	v_ashrrev_i32_e32 v145, 31, v144
	v_lshlrev_b64 v[146:147], 12, v[148:149]
	v_lshl_add_u64 v[150:151], v[128:129], 0, v[146:147]
	v_lshlrev_b64 v[146:147], 2, v[144:145]
	v_lshl_add_u64 v[144:145], v[150:151], 0, v[146:147]
	v_add_co_u32_e32 v224, vcc, 0x10000, v144
	s_nop 1
	v_addc_co_u32_e32 v225, vcc, 0, v145, vcc
	v_add_co_u32_e32 v226, vcc, 0x20000, v144
	s_nop 1
	v_addc_co_u32_e32 v227, vcc, 0, v145, vcc
	global_load_dwordx4 v[164:167], v[144:145], off
	global_load_dwordx4 v[170:173], v[144:145], off offset:64
	global_load_dwordx4 v[174:177], v[144:145], off offset:512
	global_load_dwordx4 v[178:181], v[144:145], off offset:576
	global_load_dwordx4 v[182:185], v[224:225], off
	global_load_dwordx4 v[190:193], v[224:225], off offset:64
	global_load_dwordx4 v[198:201], v[224:225], off offset:512
	global_load_dwordx4 v[202:205], v[224:225], off offset:576
	global_load_dwordx4 v[206:209], v[226:227], off
	global_load_dwordx4 v[210:213], v[226:227], off offset:64
	global_load_dwordx4 v[214:217], v[226:227], off offset:512
	global_load_dwordx4 v[218:221], v[226:227], off offset:576
	s_waitcnt vmcnt(11)
	v_pk_add_f32 v[126:127], v[126:127], v[166:167]
	v_pk_add_f32 v[124:125], v[124:125], v[164:165]
	global_store_dwordx4 v[144:145], v[124:127], off
	s_waitcnt vmcnt(11)
	v_pk_add_f32 v[122:123], v[122:123], v[172:173]
	v_pk_add_f32 v[120:121], v[120:121], v[170:171]
	global_store_dwordx4 v[144:145], v[120:123], off offset:64
	s_waitcnt vmcnt(11)
	v_pk_add_f32 v[118:119], v[118:119], v[176:177]
	v_pk_add_f32 v[116:117], v[116:117], v[174:175]
	global_store_dwordx4 v[144:145], v[116:119], off offset:512
	s_waitcnt vmcnt(11)
	v_pk_add_f32 v[114:115], v[114:115], v[180:181]
	v_pk_add_f32 v[112:113], v[112:113], v[178:179]
	global_store_dwordx4 v[144:145], v[112:115], off offset:576
	s_waitcnt vmcnt(11)
	v_pk_add_f32 v[110:111], v[110:111], v[184:185]
	v_pk_add_f32 v[108:109], v[108:109], v[182:183]
	global_store_dwordx4 v[224:225], v[108:111], off
	s_waitcnt vmcnt(11)
	v_pk_add_f32 v[106:107], v[106:107], v[192:193]
	v_pk_add_f32 v[104:105], v[104:105], v[190:191]
	global_store_dwordx4 v[224:225], v[104:107], off offset:64
	s_waitcnt vmcnt(11)
	v_pk_add_f32 v[102:103], v[102:103], v[200:201]
	v_pk_add_f32 v[100:101], v[100:101], v[198:199]
	global_store_dwordx4 v[224:225], v[100:103], off offset:512
	s_waitcnt vmcnt(11)
	v_pk_add_f32 v[98:99], v[98:99], v[204:205]
	v_pk_add_f32 v[96:97], v[96:97], v[202:203]
	global_store_dwordx4 v[224:225], v[96:99], off offset:576
	s_waitcnt vmcnt(11)
	v_pk_add_f32 v[94:95], v[94:95], v[208:209]
	v_pk_add_f32 v[92:93], v[92:93], v[206:207]
	global_store_dwordx4 v[226:227], v[92:95], off
	s_waitcnt vmcnt(11)
	v_pk_add_f32 v[90:91], v[90:91], v[212:213]
	v_pk_add_f32 v[88:89], v[88:89], v[210:211]
	global_store_dwordx4 v[226:227], v[88:91], off offset:64
	s_waitcnt vmcnt(11)
	v_pk_add_f32 v[86:87], v[86:87], v[216:217]
	v_pk_add_f32 v[84:85], v[84:85], v[214:215]
	global_store_dwordx4 v[226:227], v[84:87], off offset:512
	s_waitcnt vmcnt(11)
	v_pk_add_f32 v[82:83], v[82:83], v[220:221]
	v_pk_add_f32 v[80:81], v[80:81], v[218:219]
	global_store_dwordx4 v[226:227], v[80:83], off offset:576
	v_add_co_u32_e32 v222, vcc, 0x30000, v144
	s_nop 1
	v_addc_co_u32_e32 v223, vcc, 0, v145, vcc
	v_add_co_u32_e32 v224, vcc, 0x80000, v144
	s_nop 1
	v_addc_co_u32_e32 v225, vcc, 0, v145, vcc
	v_add_co_u32_e32 v226, vcc, 0x90000, v144
	s_nop 1
	v_addc_co_u32_e32 v227, vcc, 0, v145, vcc
	global_load_dwordx4 v[164:167], v[222:223], off
	global_load_dwordx4 v[170:173], v[222:223], off offset:64
	global_load_dwordx4 v[174:177], v[222:223], off offset:512
	global_load_dwordx4 v[178:181], v[222:223], off offset:576
	global_load_dwordx4 v[182:185], v[224:225], off
	global_load_dwordx4 v[190:193], v[224:225], off offset:64
	global_load_dwordx4 v[198:201], v[224:225], off offset:512
	global_load_dwordx4 v[202:205], v[224:225], off offset:576
	global_load_dwordx4 v[206:209], v[226:227], off
	global_load_dwordx4 v[210:213], v[226:227], off offset:64
	global_load_dwordx4 v[214:217], v[226:227], off offset:512
	global_load_dwordx4 v[218:221], v[226:227], off offset:576
	s_waitcnt vmcnt(11)
	v_pk_add_f32 v[78:79], v[78:79], v[166:167]
	v_pk_add_f32 v[76:77], v[76:77], v[164:165]
	global_store_dwordx4 v[222:223], v[76:79], off
	s_waitcnt vmcnt(11)
	v_pk_add_f32 v[74:75], v[74:75], v[172:173]
	v_pk_add_f32 v[72:73], v[72:73], v[170:171]
	global_store_dwordx4 v[222:223], v[72:75], off offset:64
	s_waitcnt vmcnt(11)
	v_pk_add_f32 v[70:71], v[70:71], v[176:177]
	v_pk_add_f32 v[68:69], v[68:69], v[174:175]
	global_store_dwordx4 v[222:223], v[68:71], off offset:512
	s_waitcnt vmcnt(11)
	v_pk_add_f32 v[66:67], v[66:67], v[180:181]
	v_pk_add_f32 v[64:65], v[64:65], v[178:179]
	global_store_dwordx4 v[222:223], v[64:67], off offset:576
	s_waitcnt vmcnt(11)
	v_pk_add_f32 v[62:63], v[62:63], v[184:185]
	v_pk_add_f32 v[60:61], v[60:61], v[182:183]
	global_store_dwordx4 v[224:225], v[60:63], off
	s_waitcnt vmcnt(11)
	v_pk_add_f32 v[58:59], v[58:59], v[192:193]
	v_pk_add_f32 v[56:57], v[56:57], v[190:191]
	global_store_dwordx4 v[224:225], v[56:59], off offset:64
	s_waitcnt vmcnt(11)
	v_pk_add_f32 v[54:55], v[54:55], v[200:201]
	v_pk_add_f32 v[52:53], v[52:53], v[198:199]
	global_store_dwordx4 v[224:225], v[52:55], off offset:512
	s_waitcnt vmcnt(11)
	v_pk_add_f32 v[50:51], v[50:51], v[204:205]
	v_pk_add_f32 v[48:49], v[48:49], v[202:203]
	global_store_dwordx4 v[224:225], v[48:51], off offset:576
	s_waitcnt vmcnt(11)
	v_pk_add_f32 v[46:47], v[46:47], v[208:209]
	v_pk_add_f32 v[44:45], v[44:45], v[206:207]
	global_store_dwordx4 v[226:227], v[44:47], off
	s_waitcnt vmcnt(11)
	v_pk_add_f32 v[42:43], v[42:43], v[212:213]
	v_pk_add_f32 v[40:41], v[40:41], v[210:211]
	global_store_dwordx4 v[226:227], v[40:43], off offset:64
	s_waitcnt vmcnt(11)
	v_pk_add_f32 v[38:39], v[38:39], v[216:217]
	v_pk_add_f32 v[36:37], v[36:37], v[214:215]
	global_store_dwordx4 v[226:227], v[36:39], off offset:512
	s_waitcnt vmcnt(11)
	v_pk_add_f32 v[34:35], v[34:35], v[220:221]
	v_pk_add_f32 v[32:33], v[32:33], v[218:219]
	global_store_dwordx4 v[226:227], v[32:35], off offset:576
	v_add_co_u32_e32 v222, vcc, 0xa0000, v144
	s_nop 1
	v_addc_co_u32_e32 v223, vcc, 0, v145, vcc
	v_add_co_u32_e32 v224, vcc, 0xb0000, v144
	s_nop 1
	v_addc_co_u32_e32 v225, vcc, 0, v145, vcc
	global_load_dwordx4 v[164:167], v[222:223], off
	global_load_dwordx4 v[170:173], v[222:223], off offset:64
	global_load_dwordx4 v[174:177], v[222:223], off offset:512
	global_load_dwordx4 v[178:181], v[222:223], off offset:576
	global_load_dwordx4 v[182:185], v[224:225], off
	global_load_dwordx4 v[190:193], v[224:225], off offset:64
	global_load_dwordx4 v[198:201], v[224:225], off offset:512
	global_load_dwordx4 v[202:205], v[224:225], off offset:576
	s_waitcnt vmcnt(7)
	v_pk_add_f32 v[30:31], v[30:31], v[166:167]
	v_pk_add_f32 v[28:29], v[28:29], v[164:165]
	global_store_dwordx4 v[222:223], v[28:31], off
	s_waitcnt vmcnt(7)
	v_pk_add_f32 v[26:27], v[26:27], v[172:173]
	v_pk_add_f32 v[24:25], v[24:25], v[170:171]
	global_store_dwordx4 v[222:223], v[24:27], off offset:64
	s_waitcnt vmcnt(7)
	v_pk_add_f32 v[22:23], v[22:23], v[176:177]
	v_pk_add_f32 v[20:21], v[20:21], v[174:175]
	global_store_dwordx4 v[222:223], v[20:23], off offset:512
	s_waitcnt vmcnt(7)
	v_pk_add_f32 v[18:19], v[18:19], v[180:181]
	v_pk_add_f32 v[16:17], v[16:17], v[178:179]
	global_store_dwordx4 v[222:223], v[16:19], off offset:576
	s_waitcnt vmcnt(7)
	v_pk_add_f32 v[14:15], v[14:15], v[184:185]
	v_pk_add_f32 v[12:13], v[12:13], v[182:183]
	global_store_dwordx4 v[224:225], v[12:15], off
	s_waitcnt vmcnt(7)
	v_pk_add_f32 v[10:11], v[10:11], v[192:193]
	v_pk_add_f32 v[8:9], v[8:9], v[190:191]
	global_store_dwordx4 v[224:225], v[8:11], off offset:64
	s_waitcnt vmcnt(7)
	v_pk_add_f32 v[6:7], v[6:7], v[200:201]
	v_pk_add_f32 v[4:5], v[4:5], v[198:199]
	global_store_dwordx4 v[224:225], v[4:7], off offset:512
	s_waitcnt vmcnt(7)
	v_pk_add_f32 v[2:3], v[2:3], v[204:205]
	v_pk_add_f32 v[0:1], v[0:1], v[202:203]
	global_store_dwordx4 v[224:225], v[0:3], off offset:576
	s_mov_b64 s[12:13], 0x80000
	s_mov_b32 s3, 0xa0000
	s_mov_b64 s[12:13], 0x90000
	s_mov_b64 s[12:13], 0xa0000
	s_mov_b32 s3, 0xb0000
	s_mov_b64 s[12:13], 0xb0000
	s_andn2_b64 vcc, exec, s[4:5]
	s_mov_b64 s[12:13], -1
	s_cbranch_vccnz .LBB0_1606
	s_andn2_b64 vcc, exec, s[6:7]
	s_cbranch_vccnz .LBB0_1605
	s_barrier
	s_branch .LBB0_1605

.LBB0_1870:
	v_lshl_add_u32 v148, s29, 8, v151
	v_lshl_or_b32 v144, s28, 8, v153
	v_ashrrev_i32_e32 v149, 31, v148
	v_ashrrev_i32_e32 v145, 31, v144
	v_lshlrev_b64 v[146:147], 12, v[148:149]
	v_lshl_add_u64 v[156:157], v[128:129], 0, v[146:147]
	v_lshlrev_b64 v[146:147], 2, v[144:145]
	v_lshl_add_u64 v[144:145], v[156:157], 0, v[146:147]
	v_add_co_u32_e32 v220, vcc, 0x10000, v144
	s_nop 1
	v_addc_co_u32_e32 v221, vcc, 0, v145, vcc
	v_add_co_u32_e32 v222, vcc, 0x20000, v144
	s_nop 1
	v_addc_co_u32_e32 v223, vcc, 0, v145, vcc
	global_load_dwordx4 v[156:159], v[144:145], off
	global_load_dwordx4 v[164:167], v[144:145], off offset:64
	global_load_dwordx4 v[170:173], v[144:145], off offset:512
	global_load_dwordx4 v[174:177], v[144:145], off offset:576
	global_load_dwordx4 v[178:181], v[220:221], off
	global_load_dwordx4 v[182:185], v[220:221], off offset:64
	global_load_dwordx4 v[190:193], v[220:221], off offset:512
	global_load_dwordx4 v[198:201], v[220:221], off offset:576
	global_load_dwordx4 v[202:205], v[222:223], off
	global_load_dwordx4 v[206:209], v[222:223], off offset:64
	global_load_dwordx4 v[210:213], v[222:223], off offset:512
	global_load_dwordx4 v[214:217], v[222:223], off offset:576
	s_waitcnt vmcnt(11)
	v_pk_fma_f32 v[126:127], v[126:127], 0.5, v[158:159] op_sel_hi:[1,0,1]
	v_pk_fma_f32 v[124:125], v[124:125], 0.5, v[156:157] op_sel_hi:[1,0,1]
	global_store_dwordx4 v[144:145], v[124:127], off
	s_waitcnt vmcnt(11)
	v_pk_fma_f32 v[122:123], v[122:123], 0.5, v[166:167] op_sel_hi:[1,0,1]
	v_pk_fma_f32 v[120:121], v[120:121], 0.5, v[164:165] op_sel_hi:[1,0,1]
	global_store_dwordx4 v[144:145], v[120:123], off offset:64
	s_waitcnt vmcnt(11)
	v_pk_fma_f32 v[118:119], v[118:119], 0.5, v[172:173] op_sel_hi:[1,0,1]
	v_pk_fma_f32 v[116:117], v[116:117], 0.5, v[170:171] op_sel_hi:[1,0,1]
	global_store_dwordx4 v[144:145], v[116:119], off offset:512
	s_waitcnt vmcnt(11)
	v_pk_fma_f32 v[114:115], v[114:115], 0.5, v[176:177] op_sel_hi:[1,0,1]
	v_pk_fma_f32 v[112:113], v[112:113], 0.5, v[174:175] op_sel_hi:[1,0,1]
	global_store_dwordx4 v[144:145], v[112:115], off offset:576
	s_waitcnt vmcnt(11)
	v_pk_fma_f32 v[110:111], v[110:111], 0.5, v[180:181] op_sel_hi:[1,0,1]
	v_pk_fma_f32 v[108:109], v[108:109], 0.5, v[178:179] op_sel_hi:[1,0,1]
	global_store_dwordx4 v[220:221], v[108:111], off
	s_waitcnt vmcnt(11)
	v_pk_fma_f32 v[106:107], v[106:107], 0.5, v[184:185] op_sel_hi:[1,0,1]
	v_pk_fma_f32 v[104:105], v[104:105], 0.5, v[182:183] op_sel_hi:[1,0,1]
	global_store_dwordx4 v[220:221], v[104:107], off offset:64
	s_waitcnt vmcnt(11)
	v_pk_fma_f32 v[102:103], v[102:103], 0.5, v[192:193] op_sel_hi:[1,0,1]
	v_pk_fma_f32 v[100:101], v[100:101], 0.5, v[190:191] op_sel_hi:[1,0,1]
	global_store_dwordx4 v[220:221], v[100:103], off offset:512
	s_waitcnt vmcnt(11)
	v_pk_fma_f32 v[98:99], v[98:99], 0.5, v[200:201] op_sel_hi:[1,0,1]
	v_pk_fma_f32 v[96:97], v[96:97], 0.5, v[198:199] op_sel_hi:[1,0,1]
	global_store_dwordx4 v[220:221], v[96:99], off offset:576
	s_waitcnt vmcnt(11)
	v_pk_fma_f32 v[94:95], v[94:95], 0.5, v[204:205] op_sel_hi:[1,0,1]
	v_pk_fma_f32 v[92:93], v[92:93], 0.5, v[202:203] op_sel_hi:[1,0,1]
	global_store_dwordx4 v[222:223], v[92:95], off
	s_waitcnt vmcnt(11)
	v_pk_fma_f32 v[90:91], v[90:91], 0.5, v[208:209] op_sel_hi:[1,0,1]
	v_pk_fma_f32 v[88:89], v[88:89], 0.5, v[206:207] op_sel_hi:[1,0,1]
	global_store_dwordx4 v[222:223], v[88:91], off offset:64
	s_waitcnt vmcnt(11)
	v_pk_fma_f32 v[86:87], v[86:87], 0.5, v[212:213] op_sel_hi:[1,0,1]
	v_pk_fma_f32 v[84:85], v[84:85], 0.5, v[210:211] op_sel_hi:[1,0,1]
	global_store_dwordx4 v[222:223], v[84:87], off offset:512
	s_waitcnt vmcnt(11)
	v_pk_fma_f32 v[82:83], v[82:83], 0.5, v[216:217] op_sel_hi:[1,0,1]
	v_pk_fma_f32 v[80:81], v[80:81], 0.5, v[214:215] op_sel_hi:[1,0,1]
	global_store_dwordx4 v[222:223], v[80:83], off offset:576
	v_add_co_u32_e32 v218, vcc, 0x30000, v144
	s_nop 1
	v_addc_co_u32_e32 v219, vcc, 0, v145, vcc
	v_add_co_u32_e32 v220, vcc, 0x80000, v144
	s_nop 1
	v_addc_co_u32_e32 v221, vcc, 0, v145, vcc
	v_add_co_u32_e32 v222, vcc, 0x90000, v144
	s_nop 1
	v_addc_co_u32_e32 v223, vcc, 0, v145, vcc
	global_load_dwordx4 v[156:159], v[218:219], off
	global_load_dwordx4 v[164:167], v[218:219], off offset:64
	global_load_dwordx4 v[170:173], v[218:219], off offset:512
	global_load_dwordx4 v[174:177], v[218:219], off offset:576
	global_load_dwordx4 v[178:181], v[220:221], off
	global_load_dwordx4 v[182:185], v[220:221], off offset:64
	global_load_dwordx4 v[190:193], v[220:221], off offset:512
	global_load_dwordx4 v[198:201], v[220:221], off offset:576
	global_load_dwordx4 v[202:205], v[222:223], off
	global_load_dwordx4 v[206:209], v[222:223], off offset:64
	global_load_dwordx4 v[210:213], v[222:223], off offset:512
	global_load_dwordx4 v[214:217], v[222:223], off offset:576
	s_waitcnt vmcnt(11)
	v_pk_fma_f32 v[78:79], v[78:79], 0.5, v[158:159] op_sel_hi:[1,0,1]
	v_pk_fma_f32 v[76:77], v[76:77], 0.5, v[156:157] op_sel_hi:[1,0,1]
	global_store_dwordx4 v[218:219], v[76:79], off
	s_waitcnt vmcnt(11)
	v_pk_fma_f32 v[74:75], v[74:75], 0.5, v[166:167] op_sel_hi:[1,0,1]
	v_pk_fma_f32 v[72:73], v[72:73], 0.5, v[164:165] op_sel_hi:[1,0,1]
	global_store_dwordx4 v[218:219], v[72:75], off offset:64
	s_waitcnt vmcnt(11)
	v_pk_fma_f32 v[70:71], v[70:71], 0.5, v[172:173] op_sel_hi:[1,0,1]
	v_pk_fma_f32 v[68:69], v[68:69], 0.5, v[170:171] op_sel_hi:[1,0,1]
	global_store_dwordx4 v[218:219], v[68:71], off offset:512
	s_waitcnt vmcnt(11)
	v_pk_fma_f32 v[66:67], v[66:67], 0.5, v[176:177] op_sel_hi:[1,0,1]
	v_pk_fma_f32 v[64:65], v[64:65], 0.5, v[174:175] op_sel_hi:[1,0,1]
	global_store_dwordx4 v[218:219], v[64:67], off offset:576
	s_waitcnt vmcnt(11)
	v_pk_fma_f32 v[62:63], v[62:63], 0.5, v[180:181] op_sel_hi:[1,0,1]
	v_pk_fma_f32 v[60:61], v[60:61], 0.5, v[178:179] op_sel_hi:[1,0,1]
	global_store_dwordx4 v[220:221], v[60:63], off
	s_waitcnt vmcnt(11)
	v_pk_fma_f32 v[58:59], v[58:59], 0.5, v[184:185] op_sel_hi:[1,0,1]
	v_pk_fma_f32 v[56:57], v[56:57], 0.5, v[182:183] op_sel_hi:[1,0,1]
	global_store_dwordx4 v[220:221], v[56:59], off offset:64
	s_waitcnt vmcnt(11)
	v_pk_fma_f32 v[54:55], v[54:55], 0.5, v[192:193] op_sel_hi:[1,0,1]
	v_pk_fma_f32 v[52:53], v[52:53], 0.5, v[190:191] op_sel_hi:[1,0,1]
	global_store_dwordx4 v[220:221], v[52:55], off offset:512
	s_waitcnt vmcnt(11)
	v_pk_fma_f32 v[50:51], v[50:51], 0.5, v[200:201] op_sel_hi:[1,0,1]
	v_pk_fma_f32 v[48:49], v[48:49], 0.5, v[198:199] op_sel_hi:[1,0,1]
	global_store_dwordx4 v[220:221], v[48:51], off offset:576
	s_waitcnt vmcnt(11)
	v_pk_fma_f32 v[46:47], v[46:47], 0.5, v[204:205] op_sel_hi:[1,0,1]
	v_pk_fma_f32 v[44:45], v[44:45], 0.5, v[202:203] op_sel_hi:[1,0,1]
	global_store_dwordx4 v[222:223], v[44:47], off
	s_waitcnt vmcnt(11)
	v_pk_fma_f32 v[42:43], v[42:43], 0.5, v[208:209] op_sel_hi:[1,0,1]
	v_pk_fma_f32 v[40:41], v[40:41], 0.5, v[206:207] op_sel_hi:[1,0,1]
	global_store_dwordx4 v[222:223], v[40:43], off offset:64
	s_waitcnt vmcnt(11)
	v_pk_fma_f32 v[38:39], v[38:39], 0.5, v[212:213] op_sel_hi:[1,0,1]
	v_pk_fma_f32 v[36:37], v[36:37], 0.5, v[210:211] op_sel_hi:[1,0,1]
	global_store_dwordx4 v[222:223], v[36:39], off offset:512
	s_waitcnt vmcnt(11)
	v_pk_fma_f32 v[34:35], v[34:35], 0.5, v[216:217] op_sel_hi:[1,0,1]
	v_pk_fma_f32 v[32:33], v[32:33], 0.5, v[214:215] op_sel_hi:[1,0,1]
	global_store_dwordx4 v[222:223], v[32:35], off offset:576
	v_add_co_u32_e32 v218, vcc, 0xa0000, v144
	s_nop 1
	v_addc_co_u32_e32 v219, vcc, 0, v145, vcc
	v_add_co_u32_e32 v220, vcc, 0xb0000, v144
	s_nop 1
	v_addc_co_u32_e32 v221, vcc, 0, v145, vcc
	global_load_dwordx4 v[156:159], v[218:219], off
	global_load_dwordx4 v[164:167], v[218:219], off offset:64
	global_load_dwordx4 v[170:173], v[218:219], off offset:512
	global_load_dwordx4 v[174:177], v[218:219], off offset:576
	global_load_dwordx4 v[178:181], v[220:221], off
	global_load_dwordx4 v[182:185], v[220:221], off offset:64
	global_load_dwordx4 v[190:193], v[220:221], off offset:512
	global_load_dwordx4 v[198:201], v[220:221], off offset:576
	s_waitcnt vmcnt(7)
	v_pk_fma_f32 v[30:31], v[30:31], 0.5, v[158:159] op_sel_hi:[1,0,1]
	v_pk_fma_f32 v[28:29], v[28:29], 0.5, v[156:157] op_sel_hi:[1,0,1]
	global_store_dwordx4 v[218:219], v[28:31], off
	s_waitcnt vmcnt(7)
	v_pk_fma_f32 v[26:27], v[26:27], 0.5, v[166:167] op_sel_hi:[1,0,1]
	v_pk_fma_f32 v[24:25], v[24:25], 0.5, v[164:165] op_sel_hi:[1,0,1]
	global_store_dwordx4 v[218:219], v[24:27], off offset:64
	s_waitcnt vmcnt(7)
	v_pk_fma_f32 v[22:23], v[22:23], 0.5, v[172:173] op_sel_hi:[1,0,1]
	v_pk_fma_f32 v[20:21], v[20:21], 0.5, v[170:171] op_sel_hi:[1,0,1]
	global_store_dwordx4 v[218:219], v[20:23], off offset:512
	s_waitcnt vmcnt(7)
	v_pk_fma_f32 v[18:19], v[18:19], 0.5, v[176:177] op_sel_hi:[1,0,1]
	v_pk_fma_f32 v[16:17], v[16:17], 0.5, v[174:175] op_sel_hi:[1,0,1]
	global_store_dwordx4 v[218:219], v[16:19], off offset:576
	s_waitcnt vmcnt(7)
	v_pk_fma_f32 v[14:15], v[14:15], 0.5, v[180:181] op_sel_hi:[1,0,1]
	v_pk_fma_f32 v[12:13], v[12:13], 0.5, v[178:179] op_sel_hi:[1,0,1]
	global_store_dwordx4 v[220:221], v[12:15], off
	s_waitcnt vmcnt(7)
	v_pk_fma_f32 v[10:11], v[10:11], 0.5, v[184:185] op_sel_hi:[1,0,1]
	v_pk_fma_f32 v[8:9], v[8:9], 0.5, v[182:183] op_sel_hi:[1,0,1]
	global_store_dwordx4 v[220:221], v[8:11], off offset:64
	s_waitcnt vmcnt(7)
	v_pk_fma_f32 v[6:7], v[6:7], 0.5, v[192:193] op_sel_hi:[1,0,1]
	v_pk_fma_f32 v[4:5], v[4:5], 0.5, v[190:191] op_sel_hi:[1,0,1]
	global_store_dwordx4 v[220:221], v[4:7], off offset:512
	s_waitcnt vmcnt(7)
	v_pk_fma_f32 v[2:3], v[2:3], 0.5, v[200:201] op_sel_hi:[1,0,1]
	v_pk_fma_f32 v[0:1], v[0:1], 0.5, v[198:199] op_sel_hi:[1,0,1]
	global_store_dwordx4 v[220:221], v[0:3], off offset:576
	s_mov_b64 s[2:3], 0x80000
	s_mov_b32 s44, 0xfffc0080
	s_mov_b32 s45, -1
	s_mov_b64 s[2:3], 0x90000
	s_mov_b64 s[2:3], 0xa0000
	s_mov_b32 s2, 0xa0000
	s_mov_b64 s[2:3], 0xb0000
	s_mov_b32 s2, 0xb0000
	s_mov_b64 s[2:3], -1
	s_and_b64 vcc, exec, s[4:5]
	s_cbranch_vccnz .LBB0_1855
	s_andn2_b64 vcc, exec, s[8:9]
	s_cbranch_vccnz .LBB0_1854
	s_barrier
	s_branch .LBB0_1854
